# cmp_item K-loop double-buffered (2 groups of 8 K-steps in flight); mLSTM q.k^T tile reads pipelined 3 pairs deep
# speedup vs baseline: 1.0167x; 1.0006x over previous
.LBB0_85:
	s_or_b64 exec, exec, s[12:13]
	s_lshl_b32 s12, s4, 4
	s_lshl_b32 s5, s4, 3
	v_and_b32_e32 v35, 15, v4
	s_and_b32 s12, s12, 0xf0
	s_and_b32 s15, s5, 0x180
	v_or_b32_e32 v2, s12, v35
	s_movk_i32 s2, 0xff
	s_lshl_b32 s18, s10, 9
	v_lshlrev_b32_e32 v3, 4, v2
	v_cmp_ne_u32_e32 vcc, s2, v2
	v_mov_b32_e32 v2, 0xfe0
	s_or_b32 s18, s18, s15
	s_bfe_u32 s13, s4, 0x20006
	v_cndmask_b32_e32 v2, v2, v3, vcc
	s_ashr_i32 s19, s18, 31
	v_readlane_b32 s20, v254, 46
	s_lshr_b32 s14, s4, 4
	s_lshr_b32 s5, s4, 6
	s_lshl_b64 s[16:17], s[10:11], 20
	v_lshl_or_b32 v2, s13, 12, v2
	s_lshl_b64 s[18:19], s[18:19], 1
	v_readlane_b32 s22, v254, 48
	v_mul_u32_u24_e32 v2, 0x1400, v2
	v_readlane_b32 s23, v254, 49
	s_add_u32 s18, s22, s18
	v_ashrrev_i32_e32 v5, 2, v4
	v_lshlrev_b32_e32 v2, 1, v2
	v_mov_b32_e32 v3, v0
	s_addc_u32 s19, s23, s19
	v_lshl_add_u64 v[8:9], s[18:19], 0, v[2:3]
	v_bfi_b32 v2, -16, v5, v4
	v_readlane_b32 s2, v254, 28
	v_ashrrev_i32_e32 v3, 31, v2
	s_add_u32 s16, s2, s16
	v_readlane_b32 s2, v254, 29
	v_lshlrev_b64 v[2:3], 13, v[2:3]
	s_addc_u32 s17, s2, s17
	v_bfe_u32 v1, v4, 4, 2
	v_lshl_add_u64 v[10:11], s[16:17], 0, v[2:3]
	v_mov_b32_e32 v2, 0
	v_lshlrev_b32_e32 v14, 3, v1
	v_and_b32_e32 v34, -16, v5
	v_lshl_add_u32 v15, v1, 5, 0
	v_lshlrev_b32_e32 v6, 4, v1
	v_mov_b32_e32 v7, v0
	s_mov_b32 s15, 0
	v_mov_b32_e32 v3, v2
	v_mov_b32_e32 v4, v2
	v_mov_b32_e32 v5, v2
	s_waitcnt lgkmcnt(0)
	s_barrier
	v_readlane_b32 s21, v254, 47
	v_lshl_add_u64 v[12:13], v[8:9], 0, v[6:7]
	v_add_co_u32_e32 v28, vcc, 0x18691000, v12
	s_nop 1
	v_addc_co_u32_e32 v29, vcc, 0, v13, vcc
	s_mov_b32 s16, 0x18693000
	v_add_co_u32_e32 v12, vcc, s16, v12
	s_nop 1
	v_addc_co_u32_e32 v13, vcc, 0, v13, vcc
	v_lshl_add_u64 v[30:31], v[10:11], 0, v[6:7]
	global_load_dwordx4 v[64:67], v[28:29], off
	global_load_dwordx4 v[96:99], v[30:31], off offset:-256
	global_load_dwordx4 v[68:71], v[28:29], off offset:64
	global_load_dwordx4 v[100:103], v[30:31], off offset:-192
	global_load_dwordx4 v[72:75], v[28:29], off offset:128
	global_load_dwordx4 v[104:107], v[30:31], off offset:-128
	global_load_dwordx4 v[76:79], v[28:29], off offset:192
	global_load_dwordx4 v[108:111], v[30:31], off offset:-64
	global_load_dwordx4 v[80:83], v[12:13], off offset:2048
	global_load_dwordx4 v[112:115], v[30:31], off
	global_load_dwordx4 v[84:87], v[12:13], off offset:2112
	global_load_dwordx4 v[116:119], v[30:31], off offset:64
	global_load_dwordx4 v[88:91], v[12:13], off offset:2176
	global_load_dwordx4 v[120:123], v[30:31], off offset:128
	global_load_dwordx4 v[92:95], v[12:13], off offset:2240
	global_load_dwordx4 v[124:127], v[30:31], off offset:192
	s_mov_b64 s[16:17], 0x5000
	v_lshl_add_u64 v[8:9], v[8:9], 0, s[16:17]
	v_lshl_add_u64 v[10:11], v[10:11], 0, s[82:83]
.LBB0_86:
	v_lshl_add_u64 v[12:13], v[8:9], 0, v[6:7]
	v_add_co_u32_e32 v28, vcc, 0x18691000, v12
	s_nop 1
	v_addc_co_u32_e32 v29, vcc, 0, v13, vcc
	s_mov_b32 s16, 0x18693000
	v_add_co_u32_e32 v12, vcc, s16, v12
	s_nop 1
	v_addc_co_u32_e32 v13, vcc, 0, v13, vcc
	v_lshl_add_u64 v[30:31], v[10:11], 0, v[6:7]
	global_load_dwordx4 v[164:167], v[28:29], off
	global_load_dwordx4 v[236:239], v[30:31], off offset:-256
	global_load_dwordx4 v[168:171], v[28:29], off offset:64
	global_load_dwordx4 v[240:243], v[30:31], off offset:-192
	global_load_dwordx4 v[172:175], v[28:29], off offset:128
	global_load_dwordx4 v[244:247], v[30:31], off offset:-128
	global_load_dwordx4 v[176:179], v[28:29], off offset:192
	global_load_dwordx4 v[248:251], v[30:31], off offset:-64
	global_load_dwordx4 v[180:183], v[12:13], off offset:2048
	global_load_dwordx4 v[208:211], v[30:31], off
	global_load_dwordx4 v[196:199], v[12:13], off offset:2112
	global_load_dwordx4 v[220:223], v[30:31], off offset:64
	global_load_dwordx4 v[200:203], v[12:13], off offset:2176
	global_load_dwordx4 v[40:43], v[30:31], off offset:128
	global_load_dwordx4 v[204:207], v[12:13], off offset:2240
	global_load_dwordx4 v[44:47], v[30:31], off offset:192
	s_mov_b64 s[16:17], 0x5000
	v_lshl_add_u64 v[8:9], v[8:9], 0, s[16:17]
	v_lshl_add_u64 v[10:11], v[10:11], 0, s[82:83]
	v_add_u32_e32 v36, s15, v15
	s_addk_i32 s15, 0x400
	ds_read_b128 v[128:131], v36
	ds_read_b128 v[132:135], v36 offset:16
	ds_read_b128 v[136:139], v36 offset:128
	ds_read_b128 v[140:143], v36 offset:144
	s_waitcnt vmcnt(31)
	v_lshlrev_b32_e32 v20, 16, v64
	v_and_b32_e32 v21, 0xffff0000, v64
	v_lshlrev_b32_e32 v22, 16, v65
	v_and_b32_e32 v23, 0xffff0000, v65
	v_lshlrev_b32_e32 v24, 16, v66
	v_and_b32_e32 v25, 0xffff0000, v66
	v_lshlrev_b32_e32 v26, 16, v67
	v_and_b32_e32 v27, 0xffff0000, v67
	s_waitcnt lgkmcnt(2)
	v_pk_add_f32 v[20:21], v[128:129], v[20:21]
	v_pk_add_f32 v[22:23], v[130:131], v[22:23]
	v_pk_add_f32 v[24:25], v[132:133], v[24:25]
	v_pk_add_f32 v[26:27], v[134:135], v[26:27]
	v_cvt_pk_bf16_f32 v16, v20, v21
	v_cvt_pk_bf16_f32 v17, v22, v23
	v_cvt_pk_bf16_f32 v18, v24, v25
	v_cvt_pk_bf16_f32 v19, v26, v27
	s_waitcnt vmcnt(30)
	s_nop 0
	v_mfma_f32_16x16x32_bf16 v[2:5], v[96:99], v[16:19], v[2:5]
	ds_read_b128 v[128:131], v36 offset:256
	ds_read_b128 v[132:135], v36 offset:272
	s_waitcnt vmcnt(29)
	v_lshlrev_b32_e32 v20, 16, v68
	v_and_b32_e32 v21, 0xffff0000, v68
	v_lshlrev_b32_e32 v22, 16, v69
	v_and_b32_e32 v23, 0xffff0000, v69
	v_lshlrev_b32_e32 v24, 16, v70
	v_and_b32_e32 v25, 0xffff0000, v70
	v_lshlrev_b32_e32 v26, 16, v71
	v_and_b32_e32 v27, 0xffff0000, v71
	s_waitcnt lgkmcnt(2)
	v_pk_add_f32 v[20:21], v[136:137], v[20:21]
	v_pk_add_f32 v[22:23], v[138:139], v[22:23]
	v_pk_add_f32 v[24:25], v[140:141], v[24:25]
	v_pk_add_f32 v[26:27], v[142:143], v[26:27]
	v_cvt_pk_bf16_f32 v16, v20, v21
	v_cvt_pk_bf16_f32 v17, v22, v23
	v_cvt_pk_bf16_f32 v18, v24, v25
	v_cvt_pk_bf16_f32 v19, v26, v27
	s_waitcnt vmcnt(28)
	s_nop 0
	v_mfma_f32_16x16x32_bf16 v[2:5], v[100:103], v[16:19], v[2:5]
	ds_read_b128 v[136:139], v36 offset:384
	ds_read_b128 v[140:143], v36 offset:400
	s_waitcnt vmcnt(27)
	v_lshlrev_b32_e32 v20, 16, v72
	v_and_b32_e32 v21, 0xffff0000, v72
	v_lshlrev_b32_e32 v22, 16, v73
	v_and_b32_e32 v23, 0xffff0000, v73
	v_lshlrev_b32_e32 v24, 16, v74
	v_and_b32_e32 v25, 0xffff0000, v74
	v_lshlrev_b32_e32 v26, 16, v75
	v_and_b32_e32 v27, 0xffff0000, v75
	s_waitcnt lgkmcnt(2)
	v_pk_add_f32 v[20:21], v[128:129], v[20:21]
	v_pk_add_f32 v[22:23], v[130:131], v[22:23]
	v_pk_add_f32 v[24:25], v[132:133], v[24:25]
	v_pk_add_f32 v[26:27], v[134:135], v[26:27]
	v_cvt_pk_bf16_f32 v16, v20, v21
	v_cvt_pk_bf16_f32 v17, v22, v23
	v_cvt_pk_bf16_f32 v18, v24, v25
	v_cvt_pk_bf16_f32 v19, v26, v27
	s_waitcnt vmcnt(26)
	s_nop 0
	v_mfma_f32_16x16x32_bf16 v[2:5], v[104:107], v[16:19], v[2:5]
	ds_read_b128 v[128:131], v36 offset:512
	ds_read_b128 v[132:135], v36 offset:528
	s_waitcnt vmcnt(25)
	v_lshlrev_b32_e32 v20, 16, v76
	v_and_b32_e32 v21, 0xffff0000, v76
	v_lshlrev_b32_e32 v22, 16, v77
	v_and_b32_e32 v23, 0xffff0000, v77
	v_lshlrev_b32_e32 v24, 16, v78
	v_and_b32_e32 v25, 0xffff0000, v78
	v_lshlrev_b32_e32 v26, 16, v79
	v_and_b32_e32 v27, 0xffff0000, v79
	s_waitcnt lgkmcnt(2)
	v_pk_add_f32 v[20:21], v[136:137], v[20:21]
	v_pk_add_f32 v[22:23], v[138:139], v[22:23]
	v_pk_add_f32 v[24:25], v[140:141], v[24:25]
	v_pk_add_f32 v[26:27], v[142:143], v[26:27]
	v_cvt_pk_bf16_f32 v16, v20, v21
	v_cvt_pk_bf16_f32 v17, v22, v23
	v_cvt_pk_bf16_f32 v18, v24, v25
	v_cvt_pk_bf16_f32 v19, v26, v27
	s_waitcnt vmcnt(24)
	s_nop 0
	v_mfma_f32_16x16x32_bf16 v[2:5], v[108:111], v[16:19], v[2:5]
	ds_read_b128 v[136:139], v36 offset:640
	ds_read_b128 v[140:143], v36 offset:656
	s_waitcnt vmcnt(23)
	v_lshlrev_b32_e32 v20, 16, v80
	v_and_b32_e32 v21, 0xffff0000, v80
	v_lshlrev_b32_e32 v22, 16, v81
	v_and_b32_e32 v23, 0xffff0000, v81
	v_lshlrev_b32_e32 v24, 16, v82
	v_and_b32_e32 v25, 0xffff0000, v82
	v_lshlrev_b32_e32 v26, 16, v83
	v_and_b32_e32 v27, 0xffff0000, v83
	s_waitcnt lgkmcnt(2)
	v_pk_add_f32 v[20:21], v[128:129], v[20:21]
	v_pk_add_f32 v[22:23], v[130:131], v[22:23]
	v_pk_add_f32 v[24:25], v[132:133], v[24:25]
	v_pk_add_f32 v[26:27], v[134:135], v[26:27]
	v_cvt_pk_bf16_f32 v16, v20, v21
	v_cvt_pk_bf16_f32 v17, v22, v23
	v_cvt_pk_bf16_f32 v18, v24, v25
	v_cvt_pk_bf16_f32 v19, v26, v27
	s_waitcnt vmcnt(22)
	s_nop 0
	v_mfma_f32_16x16x32_bf16 v[2:5], v[112:115], v[16:19], v[2:5]
	ds_read_b128 v[128:131], v36 offset:768
	ds_read_b128 v[132:135], v36 offset:784
	s_waitcnt vmcnt(21)
	v_lshlrev_b32_e32 v20, 16, v84
	v_and_b32_e32 v21, 0xffff0000, v84
	v_lshlrev_b32_e32 v22, 16, v85
	v_and_b32_e32 v23, 0xffff0000, v85
	v_lshlrev_b32_e32 v24, 16, v86
	v_and_b32_e32 v25, 0xffff0000, v86
	v_lshlrev_b32_e32 v26, 16, v87
	v_and_b32_e32 v27, 0xffff0000, v87
	s_waitcnt lgkmcnt(2)
	v_pk_add_f32 v[20:21], v[136:137], v[20:21]
	v_pk_add_f32 v[22:23], v[138:139], v[22:23]
	v_pk_add_f32 v[24:25], v[140:141], v[24:25]
	v_pk_add_f32 v[26:27], v[142:143], v[26:27]
	v_cvt_pk_bf16_f32 v16, v20, v21
	v_cvt_pk_bf16_f32 v17, v22, v23
	v_cvt_pk_bf16_f32 v18, v24, v25
	v_cvt_pk_bf16_f32 v19, v26, v27
	s_waitcnt vmcnt(20)
	s_nop 0
	v_mfma_f32_16x16x32_bf16 v[2:5], v[116:119], v[16:19], v[2:5]
	ds_read_b128 v[136:139], v36 offset:896
	ds_read_b128 v[140:143], v36 offset:912
	s_waitcnt vmcnt(19)
	v_lshlrev_b32_e32 v20, 16, v88
	v_and_b32_e32 v21, 0xffff0000, v88
	v_lshlrev_b32_e32 v22, 16, v89
	v_and_b32_e32 v23, 0xffff0000, v89
	v_lshlrev_b32_e32 v24, 16, v90
	v_and_b32_e32 v25, 0xffff0000, v90
	v_lshlrev_b32_e32 v26, 16, v91
	v_and_b32_e32 v27, 0xffff0000, v91
	s_waitcnt lgkmcnt(2)
	v_pk_add_f32 v[20:21], v[128:129], v[20:21]
	v_pk_add_f32 v[22:23], v[130:131], v[22:23]
	v_pk_add_f32 v[24:25], v[132:133], v[24:25]
	v_pk_add_f32 v[26:27], v[134:135], v[26:27]
	v_cvt_pk_bf16_f32 v16, v20, v21
	v_cvt_pk_bf16_f32 v17, v22, v23
	v_cvt_pk_bf16_f32 v18, v24, v25
	v_cvt_pk_bf16_f32 v19, v26, v27
	s_waitcnt vmcnt(18)
	s_nop 0
	v_mfma_f32_16x16x32_bf16 v[2:5], v[120:123], v[16:19], v[2:5]
	s_waitcnt vmcnt(17)
	v_lshlrev_b32_e32 v20, 16, v92
	v_and_b32_e32 v21, 0xffff0000, v92
	v_lshlrev_b32_e32 v22, 16, v93
	v_and_b32_e32 v23, 0xffff0000, v93
	v_lshlrev_b32_e32 v24, 16, v94
	v_and_b32_e32 v25, 0xffff0000, v94
	v_lshlrev_b32_e32 v26, 16, v95
	v_and_b32_e32 v27, 0xffff0000, v95
	s_waitcnt lgkmcnt(0)
	v_pk_add_f32 v[20:21], v[136:137], v[20:21]
	v_pk_add_f32 v[22:23], v[138:139], v[22:23]
	v_pk_add_f32 v[24:25], v[140:141], v[24:25]
	v_pk_add_f32 v[26:27], v[142:143], v[26:27]
	v_cvt_pk_bf16_f32 v16, v20, v21
	v_cvt_pk_bf16_f32 v17, v22, v23
	v_cvt_pk_bf16_f32 v18, v24, v25
	v_cvt_pk_bf16_f32 v19, v26, v27
	s_waitcnt vmcnt(16)
	s_nop 0
	v_mfma_f32_16x16x32_bf16 v[2:5], v[124:127], v[16:19], v[2:5]
	s_cmpk_eq_i32 s15, 0x3c00
	s_cbranch_scc1 .Lmy_cmp_last
	v_lshl_add_u64 v[12:13], v[8:9], 0, v[6:7]
	v_add_co_u32_e32 v28, vcc, 0x18691000, v12
	s_nop 1
	v_addc_co_u32_e32 v29, vcc, 0, v13, vcc
	s_mov_b32 s16, 0x18693000
	v_add_co_u32_e32 v12, vcc, s16, v12
	s_nop 1
	v_addc_co_u32_e32 v13, vcc, 0, v13, vcc
	v_lshl_add_u64 v[30:31], v[10:11], 0, v[6:7]
	global_load_dwordx4 v[64:67], v[28:29], off
	global_load_dwordx4 v[96:99], v[30:31], off offset:-256
	global_load_dwordx4 v[68:71], v[28:29], off offset:64
	global_load_dwordx4 v[100:103], v[30:31], off offset:-192
	global_load_dwordx4 v[72:75], v[28:29], off offset:128
	global_load_dwordx4 v[104:107], v[30:31], off offset:-128
	global_load_dwordx4 v[76:79], v[28:29], off offset:192
	global_load_dwordx4 v[108:111], v[30:31], off offset:-64
	global_load_dwordx4 v[80:83], v[12:13], off offset:2048
	global_load_dwordx4 v[112:115], v[30:31], off
	global_load_dwordx4 v[84:87], v[12:13], off offset:2112
	global_load_dwordx4 v[116:119], v[30:31], off offset:64
	global_load_dwordx4 v[88:91], v[12:13], off offset:2176
	global_load_dwordx4 v[120:123], v[30:31], off offset:128
	global_load_dwordx4 v[92:95], v[12:13], off offset:2240
	global_load_dwordx4 v[124:127], v[30:31], off offset:192
	s_mov_b64 s[16:17], 0x5000
	v_lshl_add_u64 v[8:9], v[8:9], 0, s[16:17]
	v_lshl_add_u64 v[10:11], v[10:11], 0, s[82:83]
	s_branch .Lmy_cmp_cont

.Lmy_cmp_cont:
	v_add_u32_e32 v36, s15, v15
	s_addk_i32 s15, 0x400
	ds_read_b128 v[128:131], v36
	ds_read_b128 v[132:135], v36 offset:16
	ds_read_b128 v[136:139], v36 offset:128
	ds_read_b128 v[140:143], v36 offset:144
	s_waitcnt vmcnt(31)
	v_lshlrev_b32_e32 v20, 16, v164
	v_and_b32_e32 v21, 0xffff0000, v164
	v_lshlrev_b32_e32 v22, 16, v165
	v_and_b32_e32 v23, 0xffff0000, v165
	v_lshlrev_b32_e32 v24, 16, v166
	v_and_b32_e32 v25, 0xffff0000, v166
	v_lshlrev_b32_e32 v26, 16, v167
	v_and_b32_e32 v27, 0xffff0000, v167
	s_waitcnt lgkmcnt(2)
	v_pk_add_f32 v[20:21], v[128:129], v[20:21]
	v_pk_add_f32 v[22:23], v[130:131], v[22:23]
	v_pk_add_f32 v[24:25], v[132:133], v[24:25]
	v_pk_add_f32 v[26:27], v[134:135], v[26:27]
	v_cvt_pk_bf16_f32 v16, v20, v21
	v_cvt_pk_bf16_f32 v17, v22, v23
	v_cvt_pk_bf16_f32 v18, v24, v25
	v_cvt_pk_bf16_f32 v19, v26, v27
	s_waitcnt vmcnt(30)
	s_nop 0
	v_mfma_f32_16x16x32_bf16 v[2:5], v[236:239], v[16:19], v[2:5]
	ds_read_b128 v[128:131], v36 offset:256
	ds_read_b128 v[132:135], v36 offset:272
	s_waitcnt vmcnt(29)
	v_lshlrev_b32_e32 v20, 16, v168
	v_and_b32_e32 v21, 0xffff0000, v168
	v_lshlrev_b32_e32 v22, 16, v169
	v_and_b32_e32 v23, 0xffff0000, v169
	v_lshlrev_b32_e32 v24, 16, v170
	v_and_b32_e32 v25, 0xffff0000, v170
	v_lshlrev_b32_e32 v26, 16, v171
	v_and_b32_e32 v27, 0xffff0000, v171
	s_waitcnt lgkmcnt(2)
	v_pk_add_f32 v[20:21], v[136:137], v[20:21]
	v_pk_add_f32 v[22:23], v[138:139], v[22:23]
	v_pk_add_f32 v[24:25], v[140:141], v[24:25]
	v_pk_add_f32 v[26:27], v[142:143], v[26:27]
	v_cvt_pk_bf16_f32 v16, v20, v21
	v_cvt_pk_bf16_f32 v17, v22, v23
	v_cvt_pk_bf16_f32 v18, v24, v25
	v_cvt_pk_bf16_f32 v19, v26, v27
	s_waitcnt vmcnt(28)
	s_nop 0
	v_mfma_f32_16x16x32_bf16 v[2:5], v[240:243], v[16:19], v[2:5]
	ds_read_b128 v[136:139], v36 offset:384
	ds_read_b128 v[140:143], v36 offset:400
	s_waitcnt vmcnt(27)
	v_lshlrev_b32_e32 v20, 16, v172
	v_and_b32_e32 v21, 0xffff0000, v172
	v_lshlrev_b32_e32 v22, 16, v173
	v_and_b32_e32 v23, 0xffff0000, v173
	v_lshlrev_b32_e32 v24, 16, v174
	v_and_b32_e32 v25, 0xffff0000, v174
	v_lshlrev_b32_e32 v26, 16, v175
	v_and_b32_e32 v27, 0xffff0000, v175
	s_waitcnt lgkmcnt(2)
	v_pk_add_f32 v[20:21], v[128:129], v[20:21]
	v_pk_add_f32 v[22:23], v[130:131], v[22:23]
	v_pk_add_f32 v[24:25], v[132:133], v[24:25]
	v_pk_add_f32 v[26:27], v[134:135], v[26:27]
	v_cvt_pk_bf16_f32 v16, v20, v21
	v_cvt_pk_bf16_f32 v17, v22, v23
	v_cvt_pk_bf16_f32 v18, v24, v25
	v_cvt_pk_bf16_f32 v19, v26, v27
	s_waitcnt vmcnt(26)
	s_nop 0
	v_mfma_f32_16x16x32_bf16 v[2:5], v[244:247], v[16:19], v[2:5]
	ds_read_b128 v[128:131], v36 offset:512
	ds_read_b128 v[132:135], v36 offset:528
	s_waitcnt vmcnt(25)
	v_lshlrev_b32_e32 v20, 16, v176
	v_and_b32_e32 v21, 0xffff0000, v176
	v_lshlrev_b32_e32 v22, 16, v177
	v_and_b32_e32 v23, 0xffff0000, v177
	v_lshlrev_b32_e32 v24, 16, v178
	v_and_b32_e32 v25, 0xffff0000, v178
	v_lshlrev_b32_e32 v26, 16, v179
	v_and_b32_e32 v27, 0xffff0000, v179
	s_waitcnt lgkmcnt(2)
	v_pk_add_f32 v[20:21], v[136:137], v[20:21]
	v_pk_add_f32 v[22:23], v[138:139], v[22:23]
	v_pk_add_f32 v[24:25], v[140:141], v[24:25]
	v_pk_add_f32 v[26:27], v[142:143], v[26:27]
	v_cvt_pk_bf16_f32 v16, v20, v21
	v_cvt_pk_bf16_f32 v17, v22, v23
	v_cvt_pk_bf16_f32 v18, v24, v25
	v_cvt_pk_bf16_f32 v19, v26, v27
	s_waitcnt vmcnt(24)
	s_nop 0
	v_mfma_f32_16x16x32_bf16 v[2:5], v[248:251], v[16:19], v[2:5]
	ds_read_b128 v[136:139], v36 offset:640
	ds_read_b128 v[140:143], v36 offset:656
	s_waitcnt vmcnt(23)
	v_lshlrev_b32_e32 v20, 16, v180
	v_and_b32_e32 v21, 0xffff0000, v180
	v_lshlrev_b32_e32 v22, 16, v181
	v_and_b32_e32 v23, 0xffff0000, v181
	v_lshlrev_b32_e32 v24, 16, v182
	v_and_b32_e32 v25, 0xffff0000, v182
	v_lshlrev_b32_e32 v26, 16, v183
	v_and_b32_e32 v27, 0xffff0000, v183
	s_waitcnt lgkmcnt(2)
	v_pk_add_f32 v[20:21], v[128:129], v[20:21]
	v_pk_add_f32 v[22:23], v[130:131], v[22:23]
	v_pk_add_f32 v[24:25], v[132:133], v[24:25]
	v_pk_add_f32 v[26:27], v[134:135], v[26:27]
	v_cvt_pk_bf16_f32 v16, v20, v21
	v_cvt_pk_bf16_f32 v17, v22, v23
	v_cvt_pk_bf16_f32 v18, v24, v25
	v_cvt_pk_bf16_f32 v19, v26, v27
	s_waitcnt vmcnt(22)
	s_nop 0
	v_mfma_f32_16x16x32_bf16 v[2:5], v[208:211], v[16:19], v[2:5]
	ds_read_b128 v[128:131], v36 offset:768
	ds_read_b128 v[132:135], v36 offset:784
	s_waitcnt vmcnt(21)
	v_lshlrev_b32_e32 v20, 16, v196
	v_and_b32_e32 v21, 0xffff0000, v196
	v_lshlrev_b32_e32 v22, 16, v197
	v_and_b32_e32 v23, 0xffff0000, v197
	v_lshlrev_b32_e32 v24, 16, v198
	v_and_b32_e32 v25, 0xffff0000, v198
	v_lshlrev_b32_e32 v26, 16, v199
	v_and_b32_e32 v27, 0xffff0000, v199
	s_waitcnt lgkmcnt(2)
	v_pk_add_f32 v[20:21], v[136:137], v[20:21]
	v_pk_add_f32 v[22:23], v[138:139], v[22:23]
	v_pk_add_f32 v[24:25], v[140:141], v[24:25]
	v_pk_add_f32 v[26:27], v[142:143], v[26:27]
	v_cvt_pk_bf16_f32 v16, v20, v21
	v_cvt_pk_bf16_f32 v17, v22, v23
	v_cvt_pk_bf16_f32 v18, v24, v25
	v_cvt_pk_bf16_f32 v19, v26, v27
	s_waitcnt vmcnt(20)
	s_nop 0
	v_mfma_f32_16x16x32_bf16 v[2:5], v[220:223], v[16:19], v[2:5]
	ds_read_b128 v[136:139], v36 offset:896
	ds_read_b128 v[140:143], v36 offset:912
	s_waitcnt vmcnt(19)
	v_lshlrev_b32_e32 v20, 16, v200
	v_and_b32_e32 v21, 0xffff0000, v200
	v_lshlrev_b32_e32 v22, 16, v201
	v_and_b32_e32 v23, 0xffff0000, v201
	v_lshlrev_b32_e32 v24, 16, v202
	v_and_b32_e32 v25, 0xffff0000, v202
	v_lshlrev_b32_e32 v26, 16, v203
	v_and_b32_e32 v27, 0xffff0000, v203
	s_waitcnt lgkmcnt(2)
	v_pk_add_f32 v[20:21], v[128:129], v[20:21]
	v_pk_add_f32 v[22:23], v[130:131], v[22:23]
	v_pk_add_f32 v[24:25], v[132:133], v[24:25]
	v_pk_add_f32 v[26:27], v[134:135], v[26:27]
	v_cvt_pk_bf16_f32 v16, v20, v21
	v_cvt_pk_bf16_f32 v17, v22, v23
	v_cvt_pk_bf16_f32 v18, v24, v25
	v_cvt_pk_bf16_f32 v19, v26, v27
	s_waitcnt vmcnt(18)
	s_nop 0
	v_mfma_f32_16x16x32_bf16 v[2:5], v[40:43], v[16:19], v[2:5]
	s_waitcnt vmcnt(17)
	v_lshlrev_b32_e32 v20, 16, v204
	v_and_b32_e32 v21, 0xffff0000, v204
	v_lshlrev_b32_e32 v22, 16, v205
	v_and_b32_e32 v23, 0xffff0000, v205
	v_lshlrev_b32_e32 v24, 16, v206
	v_and_b32_e32 v25, 0xffff0000, v206
	v_lshlrev_b32_e32 v26, 16, v207
	v_and_b32_e32 v27, 0xffff0000, v207
	s_waitcnt lgkmcnt(0)
	v_pk_add_f32 v[20:21], v[136:137], v[20:21]
	v_pk_add_f32 v[22:23], v[138:139], v[22:23]
	v_pk_add_f32 v[24:25], v[140:141], v[24:25]
	v_pk_add_f32 v[26:27], v[142:143], v[26:27]
	v_cvt_pk_bf16_f32 v16, v20, v21
	v_cvt_pk_bf16_f32 v17, v22, v23
	v_cvt_pk_bf16_f32 v18, v24, v25
	v_cvt_pk_bf16_f32 v19, v26, v27
	s_waitcnt vmcnt(16)
	s_nop 0
	v_mfma_f32_16x16x32_bf16 v[2:5], v[44:47], v[16:19], v[2:5]
	s_cmpk_eq_i32 s15, 0x4000
	s_cbranch_scc0 .LBB0_86
	s_branch .Lmy_pad_cmp
.Lmy_tramp4:
	s_branch .LBB0_4
	s_nop 0
	s_nop 0
	s_nop 0
	s_nop 0
	s_nop 0
	s_nop 0
	s_nop 0
	s_nop 0
	s_nop 0
	s_nop 0
	s_nop 0
	s_nop 0
	s_nop 0
	s_nop 0
	s_nop 0
	s_nop 0
	s_nop 0
	s_nop 0
	s_nop 0
	s_nop 0
	s_nop 0
	s_nop 0
	s_nop 0
	s_nop 0
	s_nop 0
	s_nop 0
	s_nop 0
	s_nop 0
	s_nop 0
	s_nop 0
	s_nop 0
	s_nop 0
	s_nop 0
	s_nop 0
	s_nop 0
	s_nop 0
	s_nop 0
	s_nop 0
	s_nop 0
	s_nop 0
	s_nop 0

.LBB0_326:
	ds_read_b128 v[236:239], v181
	ds_read_b128 v[240:243], v181 offset:8448
	ds_read_b128 v[244:247], v181 offset:64
	ds_read_b128 v[248:251], v181 offset:8512
	ds_read_b128 v[206:209], v181 offset:128
	ds_read_b128 v[210:213], v181 offset:8576
	v_cmp_le_i32_e32 vcc, v180, v130
	v_add_u32_e32 v192, 2, v180
	v_cmp_le_i32_e64 s[34:35], v192, v130
	v_add_u32_e32 v183, -1, v183
	s_waitcnt vmcnt(23) lgkmcnt(5)
	v_mfma_f32_16x16x32_bf16 v[198:201], v[236:239], v[116:119], 0
	s_waitcnt lgkmcnt(4)
	v_mfma_f32_16x16x32_bf16 v[124:127], v[240:243], v[116:119], 0
	ds_read_b128 v[236:239], v181 offset:192
	ds_read_b128 v[240:243], v181 offset:8640
	s_waitcnt vmcnt(22) lgkmcnt(5)
	v_mfma_f32_16x16x32_bf16 v[198:201], v[244:247], v[112:115], v[198:201]
	s_waitcnt lgkmcnt(4)
	v_mfma_f32_16x16x32_bf16 v[124:127], v[248:251], v[112:115], v[124:127]
	ds_read_b128 v[244:247], v181 offset:256
	ds_read_b128 v[248:251], v181 offset:8704
	s_waitcnt vmcnt(21) lgkmcnt(5)
	v_mfma_f32_16x16x32_bf16 v[198:201], v[206:209], v[108:111], v[198:201]
	s_waitcnt lgkmcnt(4)
	v_mfma_f32_16x16x32_bf16 v[124:127], v[210:213], v[108:111], v[124:127]
	ds_read_b128 v[206:209], v181 offset:320
	ds_read_b128 v[210:213], v181 offset:8768
	s_waitcnt vmcnt(20) lgkmcnt(5)
	v_mfma_f32_16x16x32_bf16 v[198:201], v[236:239], v[104:107], v[198:201]
	s_waitcnt lgkmcnt(4)
	v_mfma_f32_16x16x32_bf16 v[124:127], v[240:243], v[104:107], v[124:127]
	ds_read_b128 v[236:239], v181 offset:384
	ds_read_b128 v[240:243], v181 offset:8832
	s_waitcnt vmcnt(19) lgkmcnt(5)
	v_mfma_f32_16x16x32_bf16 v[198:201], v[244:247], v[100:103], v[198:201]
	s_waitcnt lgkmcnt(4)
	v_mfma_f32_16x16x32_bf16 v[124:127], v[248:251], v[100:103], v[124:127]
	ds_read_b128 v[244:247], v181 offset:448
	ds_read_b128 v[248:251], v181 offset:8896
	s_waitcnt vmcnt(18) lgkmcnt(5)
	v_mfma_f32_16x16x32_bf16 v[198:201], v[206:209], v[96:99], v[198:201]
	s_waitcnt lgkmcnt(4)
	v_mfma_f32_16x16x32_bf16 v[124:127], v[210:213], v[96:99], v[124:127]
	s_waitcnt vmcnt(17) lgkmcnt(3)
	v_mfma_f32_16x16x32_bf16 v[198:201], v[236:239], v[92:95], v[198:201]
	s_waitcnt lgkmcnt(2)
	v_mfma_f32_16x16x32_bf16 v[124:127], v[240:243], v[92:95], v[124:127]
	s_waitcnt vmcnt(16) lgkmcnt(1)
	v_mfma_f32_16x16x32_bf16 v[198:201], v[244:247], v[88:91], v[198:201]
	s_waitcnt lgkmcnt(0)
	v_mfma_f32_16x16x32_bf16 v[124:127], v[248:251], v[88:91], v[124:127]
	v_add_u32_e32 v181, 0x4200, v181
	s_nop 2
	ds_read_b128 v[194:197], v179
	v_add_u32_e32 v179, 0x80, v179
	s_waitcnt lgkmcnt(0)
	v_sub_f32_e32 v185, v194, v178
	v_mul_f32_e32 v185, 0x3fb8aa3b, v185
	v_exp_f32_e32 v185, v185
	v_sub_f32_e32 v194, v196, v178
	v_mul_f32_e32 v194, 0x3fb8aa3b, v194
	v_exp_f32_e32 v194, v194
	v_cndmask_b32_e32 v185, 0, v185, vcc
	v_mul_f32_e32 v191, v198, v185
	v_fmac_f32_e32 v184, v198, v185
	v_sub_f32_e32 v185, v195, v178
	v_mul_f32_e32 v185, 0x3fb8aa3b, v185
	v_exp_f32_e32 v185, v185
	v_cmp_gt_i32_e32 vcc, v130, v180
	v_cndmask_b32_e64 v195, 0, v194, s[34:35]
	v_mov_b32_e32 v198, v199
	v_cndmask_b32_e32 v194, 0, v185, vcc
	v_mov_b32_e32 v199, v200
	v_pk_mul_f32 v[198:199], v[198:199], v[194:195]
	v_or_b32_e32 v200, 3, v180
	v_add_f32_e32 v184, v198, v184
	v_add_f32_e32 v192, v199, v184
	v_sub_f32_e32 v184, v197, v178
	v_mul_f32_e32 v184, 0x3fb8aa3b, v184
	v_exp_f32_e32 v185, v184
	v_or_b32_e32 v184, 16, v180
	v_lshl_add_u32 v194, v184, 2, s53
	ds_read_b128 v[194:197], v194
	v_cmp_le_i32_e32 vcc, v184, v130
	s_waitcnt lgkmcnt(0)
	v_sub_f32_e32 v194, v194, v178
	v_mul_f32_e32 v194, 0x3fb8aa3b, v194
	v_exp_f32_e32 v194, v194
	s_nop 0
	v_cndmask_b32_e32 v184, 0, v194, vcc
	v_cmp_le_i32_e32 vcc, v200, v1
	v_mov_b32_e32 v200, v124
	v_or_b32_e32 v194, 17, v180
	v_cndmask_b32_e32 v185, 0, v185, vcc
	v_pk_mul_f32 v[200:201], v[200:201], v[184:185]
	v_sub_f32_e32 v184, v196, v178
	v_add_f32_e32 v124, v201, v192
	v_add_f32_e32 v192, v200, v124
	v_sub_f32_e32 v124, v195, v178
	v_mul_f32_e32 v184, 0x3fb8aa3b, v184
	v_mul_f32_e32 v124, 0x3fb8aa3b, v124
	v_exp_f32_e32 v184, v184
	v_exp_f32_e32 v124, v124
	v_or_b32_e32 v185, 18, v180
	v_cmp_le_i32_e32 vcc, v185, v1
	s_nop 1
	v_cndmask_b32_e32 v185, 0, v184, vcc
	v_cmp_le_i32_e32 vcc, v194, v130
	s_nop 1
	v_cndmask_b32_e32 v184, 0, v124, vcc
	v_mov_b32_e32 v124, v125
	v_mov_b32_e32 v125, v126
	v_pk_mul_f32 v[194:195], v[124:125], v[184:185]
	v_sub_f32_e32 v125, v197, v178
	v_mul_f32_e32 v125, 0x3fb8aa3b, v125
	v_exp_f32_e32 v125, v125
	v_add_f32_e32 v124, v194, v192
	v_add_f32_e32 v184, v195, v124
	v_add_u32_e32 v124, 19, v180
	v_cmp_le_i32_e32 vcc, v124, v130
	v_cvt_pk_bf16_f32 v126, v200, v194
	v_add_u32_e32 v180, 32, v180
	v_cndmask_b32_e32 v124, 0, v125, vcc
	v_mul_f32_e32 v185, v127, v124
	v_fmac_f32_e32 v184, v127, v124
	v_cvt_pk_bf16_f32 v127, v195, v185
	ds_read_b128 v[194:197], v182
	v_cvt_pk_bf16_f32 v124, v191, v198
	v_cvt_pk_bf16_f32 v125, v199, v201
	v_cmp_eq_u32_e32 vcc, 0, v183
	v_add_u32_e32 v182, 64, v182
	s_waitcnt lgkmcnt(0)
	v_mfma_f32_16x16x32_bf16 v[120:123], v[194:197], v[124:127], v[120:123]
	s_or_b64 s[46:47], vcc, s[46:47]
	s_andn2_b64 exec, exec, s[46:47]
	s_cbranch_execnz .LBB0_326
	s_or_b64 exec, exec, s[46:47]
